# phase 1 weight-conversion jobs enumerated n-major (adjacent jobs read adjacent 256-B segments of the same source rows) instead of k-major
# baseline (speedup 1.0000x reference)
.LBB0_471:
	s_lshr_b32 s1, s10, 6
	v_cvt_f32_ubyte0_e32 v0, s1
	v_rcp_iflag_f32_e32 v0, v0
	s_load_dwordx2 s[16:17], s[18:19], 0x0
	s_sub_i32 s13, 0, s1
	s_abs_i32 s12, s2
	v_mul_f32_e32 v0, 0x4f7ffffe, v0
	v_cvt_u32_f32_e32 v0, v0
	s_ashr_i32 s11, s2, 31
	v_mov_b32_e32 v4, 0
	v_mov_b32_e32 v5, 0
	v_readfirstlane_b32 s18, v0
	s_mul_i32 s13, s13, s18
	s_mul_hi_u32 s13, s18, s13
	s_add_i32 s18, s18, s13
	s_mul_hi_u32 s13, s12, s18
	s_mul_i32 s18, s13, s1
	s_sub_i32 s12, s12, s18
	s_add_i32 s19, s13, 1
	s_sub_i32 s18, s12, s1
	s_cmp_ge_u32 s12, s1
	s_cselect_b32 s13, s19, s13
	s_cselect_b32 s12, s18, s12
	s_add_i32 s18, s13, 1
	s_cmp_ge_u32 s12, s1
	s_cselect_b32 s12, s18, s13
	s_xor_b32 s12, s12, s11
	s_sub_i32 s11, s12, s11
	s_mul_i32 s1, s11, s1
	s_sub_i32 s1, s2, s1
	s_lshl_b32 s2, s1, 5
	s_lshl_b32 s12, s11, 6
	s_lshl_b32 s1, s1, 6
	v_or_b32_e32 v1, s2, v22
	v_add_u32_e32 v2, s2, v24
	v_or_b32_e32 v0, s1, v22
	v_cndmask_b32_e64 v1, v2, v1, s[6:7]
	v_cndmask_b32_e64 v196, v1, v0, s[8:9]
	v_cmp_lt_i32_e32 vcc, -1, v196
	v_add_u32_e32 v31, s12, v23
	s_waitcnt lgkmcnt(0)
	v_lshl_add_u64 v[20:21], v[196:197], 2, s[16:17]
	v_mov_b32_e32 v0, 0
	v_mov_b32_e32 v6, 0
	v_mov_b32_e32 v7, 0
	s_and_saveexec_b64 s[8:9], vcc
	s_cbranch_execz .LBB0_473
	v_mad_i64_i32 v[2:3], s[16:17], s10, v31, 0
	v_lshl_add_u64 v[2:3], v[2:3], 2, v[20:21]
	global_load_dwordx4 v[4:7], v[2:3], off nt
